# odd_tiles conv: cross-group software prefetch of the 5 weight loads (next group issued before current group's compute, two register pools, copy-in)
# baseline (speedup 1.0000x reference)
; __device__ __forceinline__ float bflo(unsigned v) { return __uint_as_float(v << 16); }
; __device__ __forceinline__ float bfhi(unsigned v) { return __uint_as_float(v & 0xffff0000u); }
; __device__ __forceinline__ unsigned pack2(float a, float b) { return (unsigned)f2bf(a) | ((unsigned)f2bf(b) << 16); }
; __device__ void odd_tiles(int tid_, int bid_, int nblk_, const Params& p, int oi, int mode, bool skip_ctx, char* smem) {
;     ...
; #pragma unroll
;     for (int i = 0; i < 5; ++i) {
;       int e = tid + i * 256, t = e / 40, c4 = (e % 40) * 4;
;       float4 acc = *(const float4*)(p.od_conv_b + oi * DC + cb + c4);
; #pragma unroll
;       for (int j = 0; j < 4; ++j) {
;         uint2 xv = xr[i][j];
;         float4 wv = *(const float4*)(p.od_conv_w + ((size_t)oi * 4 + j) * DC + cb + c4);
;         acc.x += bflo(xv.x) * wv.x; acc.y += bfhi(xv.x) * wv.y; acc.z += bflo(xv.y) * wv.z; acc.w += bfhi(xv.y) * wv.w;
;       }
;       uint2 o;
;       o.x = pack2(acc.x, acc.y);
;       o.y = pack2(acc.z, acc.w);
;       *(uint2*)(sU + t * 168 + c4) = o;
;     }
.LBB0_100:
	s_and_b32 s30, s26, 15
	s_mul_i32 s34, s30, 0xa0
	s_lshl_b32 s22, s34, 2
	s_add_u32 s20, s89, s22
	v_readlane_b32 s64, v252, 33
	s_addc_u32 s21, s90, 0
	v_readlane_b32 s76, v252, 45
	v_readlane_b32 s77, v252, 46
	s_add_u32 s22, s76, s22
	v_lshlrev_b64 v[2:3], 2, v[96:97]
	s_addc_u32 s23, s77, 0
	v_lshl_add_u64 v[4:5], s[20:21], 0, v[2:3]
	v_lshl_add_u64 v[2:3], s[22:23], 0, v[2:3]
	s_mov_b32 s61, s1
	v_lshl_add_u64 v[10:11], v[2:3], 0, s[60:61]
	global_load_dwordx4 v[24:27], v[4:5], off
	s_nop 0
	global_load_dwordx4 v[28:31], v[10:11], off
	v_add_co_u32_e32 v20, vcc, 0x2800, v10
	s_nop 1
	v_addc_co_u32_e32 v21, vcc, 0, v11, vcc
	global_load_dwordx4 v[32:35], v[20:21], off
	v_add_co_u32_e32 v20, vcc, 0x5000, v10
	s_nop 1
	v_addc_co_u32_e32 v21, vcc, 0, v11, vcc
	global_load_dwordx4 v[36:39], v[20:21], off
	v_add_co_u32_e32 v20, vcc, 0x7800, v10
	s_nop 1
	v_addc_co_u32_e32 v21, vcc, 0, v11, vcc
	global_load_dwordx4 v[40:43], v[20:21], off
	v_lshlrev_b64 v[64:65], 2, v[98:99]
	v_lshl_add_u64 v[66:67], s[20:21], 0, v[64:65]
	v_lshl_add_u64 v[64:65], s[22:23], 0, v[64:65]
	v_lshl_add_u64 v[64:65], v[64:65], 0, s[60:61]
	global_load_dwordx4 v[44:47], v[66:67], off
	global_load_dwordx4 v[48:51], v[64:65], off
	v_add_co_u32_e32 v20, vcc, 0x2800, v64
	s_nop 1
	v_addc_co_u32_e32 v21, vcc, 0, v65, vcc
	global_load_dwordx4 v[52:55], v[20:21], off
	v_add_co_u32_e32 v20, vcc, 0x5000, v64
	s_nop 1
	v_addc_co_u32_e32 v21, vcc, 0, v65, vcc
	global_load_dwordx4 v[56:59], v[20:21], off
	v_add_co_u32_e32 v20, vcc, 0x7800, v64
	s_nop 1
	v_addc_co_u32_e32 v21, vcc, 0, v65, vcc
	global_load_dwordx4 v[60:63], v[20:21], off
	s_movk_i32 s24, 0x2000
	s_waitcnt vmcnt(8)
	v_mov_b32_e32 v2, v24
	v_mov_b32_e32 v3, v25
	v_mov_b32_e32 v4, v26
	v_mov_b32_e32 v5, v27
	v_mov_b32_e32 v6, v28
	v_mov_b32_e32 v7, v29
	v_mov_b32_e32 v8, v30
	v_mov_b32_e32 v9, v31
	v_and_b32_e32 v14, 0xffff0000, v70
	v_and_b32_e32 v15, 0xffff0000, v71
	v_lshlrev_b32_e32 v12, 16, v70
	v_lshlrev_b32_e32 v13, 16, v71
	s_movk_i32 s25, 0x5000
	s_movk_i32 s28, 0x7000
	s_movk_i32 s2, 0x2000
	v_readlane_b32 s65, v252, 34
	v_readlane_b32 s66, v252, 35
	v_readlane_b32 s67, v252, 36
	v_readlane_b32 s68, v252, 37
	v_readlane_b32 s69, v252, 38
	v_readlane_b32 s70, v252, 39
	v_readlane_b32 s71, v252, 40
	v_readlane_b32 s72, v252, 41
	v_readlane_b32 s73, v252, 42
	v_readlane_b32 s74, v252, 43
	v_readlane_b32 s75, v252, 44
	v_readlane_b32 s78, v252, 47
	v_readlane_b32 s79, v252, 48
	v_mov_b32_e32 v18, v2
	v_mov_b32_e32 v17, v8
	v_mov_b32_e32 v19, v4
	v_mov_b32_e32 v8, v7
	v_mov_b32_e32 v4, v3
	v_mov_b32_e32 v16, v6
	v_pk_fma_f32 v[6:7], v[8:9], v[14:15], v[4:5]
	v_pk_fma_f32 v[12:13], v[16:17], v[12:13], v[18:19]
	v_lshlrev_b32_e32 v9, 16, v73
	v_lshlrev_b32_e32 v8, 16, v72
	s_waitcnt vmcnt(7)
	v_mov_b32_e32 v2, v32
	v_mov_b32_e32 v3, v33
	v_mov_b32_e32 v4, v34
	v_mov_b32_e32 v5, v35
	v_mov_b32_e32 v14, v2
	v_mov_b32_e32 v15, v4
	v_pk_fma_f32 v[8:9], v[14:15], v[8:9], v[12:13]
	v_and_b32_e32 v13, 0xffff0000, v73
	v_and_b32_e32 v12, 0xffff0000, v72
	v_mov_b32_e32 v4, v3
	v_pk_fma_f32 v[6:7], v[4:5], v[12:13], v[6:7]
	v_lshlrev_b32_e32 v13, 16, v75
	v_lshlrev_b32_e32 v12, 16, v74
	s_waitcnt vmcnt(6)
	v_mov_b32_e32 v2, v36
	v_mov_b32_e32 v3, v37
	v_mov_b32_e32 v4, v38
	v_mov_b32_e32 v5, v39
	v_mov_b32_e32 v14, v2
	v_mov_b32_e32 v15, v4
	v_pk_fma_f32 v[8:9], v[14:15], v[12:13], v[8:9]
	v_and_b32_e32 v13, 0xffff0000, v75
	v_and_b32_e32 v12, 0xffff0000, v74
	v_mov_b32_e32 v4, v3
	v_pk_fma_f32 v[6:7], v[4:5], v[12:13], v[6:7]
	v_lshlrev_b32_e32 v11, 16, v77
	v_lshlrev_b32_e32 v10, 16, v76
	v_and_b32_e32 v14, 0xffff0000, v78
	v_and_b32_e32 v15, 0xffff0000, v79
	s_waitcnt vmcnt(5)
	v_mov_b32_e32 v2, v40
	v_mov_b32_e32 v3, v41
	v_mov_b32_e32 v4, v42
	v_mov_b32_e32 v5, v43
	v_mov_b32_e32 v12, v2
	v_mov_b32_e32 v13, v4
	v_pk_fma_f32 v[8:9], v[12:13], v[10:11], v[8:9]
	v_and_b32_e32 v11, 0xffff0000, v77
	v_and_b32_e32 v10, 0xffff0000, v76
	v_mov_b32_e32 v4, v3
	v_pk_fma_f32 v[2:3], v[4:5], v[10:11], v[6:7]
	v_and_b32_sdwa v1, v9, v198 dst_sel:DWORD dst_unused:UNUSED_PAD src0_sel:WORD_1 src1_sel:DWORD
	v_and_b32_sdwa v5, v3, v198 dst_sel:DWORD dst_unused:UNUSED_PAD src0_sel:WORD_1 src1_sel:DWORD
	v_and_b32_sdwa v6, v2, v198 dst_sel:DWORD dst_unused:UNUSED_PAD src0_sel:WORD_1 src1_sel:DWORD
	v_and_b32_sdwa v4, v8, v198 dst_sel:DWORD dst_unused:UNUSED_PAD src0_sel:WORD_1 src1_sel:DWORD
	v_add3_u32 v3, v3, v5, s63
	v_add3_u32 v2, v2, v6, s63
	v_add3_u32 v4, v8, v4, s63
	v_add3_u32 v1, v9, v1, s63
	v_and_b32_e32 v3, 0xffff0000, v3
	v_and_b32_e32 v2, 0xffff0000, v2
	v_or_b32_sdwa v3, v3, v1 dst_sel:DWORD dst_unused:UNUSED_PAD src0_sel:DWORD src1_sel:WORD_1
	v_or_b32_sdwa v2, v2, v4 dst_sel:DWORD dst_unused:UNUSED_PAD src0_sel:DWORD src1_sel:WORD_1
	ds_write_b64 v155, v[2:3]
	v_lshlrev_b64 v[2:3], 2, v[98:99]
	v_lshl_add_u64 v[4:5], s[20:21], 0, v[2:3]
	v_lshl_add_u64 v[2:3], s[22:23], 0, v[2:3]
	v_lshl_add_u64 v[10:11], v[2:3], 0, s[60:61]
	s_nop 0
	v_lshlrev_b64 v[64:65], 2, v[100:101]
	v_lshl_add_u64 v[66:67], s[20:21], 0, v[64:65]
	v_lshl_add_u64 v[64:65], s[22:23], 0, v[64:65]
	v_lshl_add_u64 v[64:65], v[64:65], 0, s[60:61]
	global_load_dwordx4 v[24:27], v[66:67], off
	global_load_dwordx4 v[28:31], v[64:65], off
	v_add_co_u32_e32 v20, vcc, 0x2800, v64
	s_nop 1
	v_addc_co_u32_e32 v21, vcc, 0, v65, vcc
	global_load_dwordx4 v[32:35], v[20:21], off
	v_add_co_u32_e32 v20, vcc, 0x5000, v64
	s_nop 1
	v_addc_co_u32_e32 v21, vcc, 0, v65, vcc
	global_load_dwordx4 v[36:39], v[20:21], off
	v_add_co_u32_e32 v20, vcc, 0x7800, v64
	s_nop 1
	v_addc_co_u32_e32 v21, vcc, 0, v65, vcc
	global_load_dwordx4 v[40:43], v[20:21], off
	v_lshlrev_b32_e32 v12, 16, v78
	v_lshlrev_b32_e32 v13, 16, v79
	s_waitcnt vmcnt(9)
; __device__ __forceinline__ float bflo(unsigned v) { return __uint_as_float(v << 16); }
; __device__ __forceinline__ float bfhi(unsigned v) { return __uint_as_float(v & 0xffff0000u); }
; __device__ __forceinline__ unsigned pack2(float a, float b) { return (unsigned)f2bf(a) | ((unsigned)f2bf(b) << 16); }
; __device__ void odd_tiles(int tid_, int bid_, int nblk_, const Params& p, int oi, int mode, bool skip_ctx, char* smem) {
;     ...
; #pragma unroll
;     for (int i = 0; i < 5; ++i) {
;       int e = tid + i * 256, t = e / 40, c4 = (e % 40) * 4;
;       float4 acc = *(const float4*)(p.od_conv_b + oi * DC + cb + c4);
; #pragma unroll
;       for (int j = 0; j < 4; ++j) {
;         uint2 xv = xr[i][j];
;         float4 wv = *(const float4*)(p.od_conv_w + ((size_t)oi * 4 + j) * DC + cb + c4);
;         acc.x += bflo(xv.x) * wv.x; acc.y += bfhi(xv.x) * wv.y; acc.z += bflo(xv.y) * wv.z; acc.w += bfhi(xv.y) * wv.w;
;       }
;       uint2 o;
;       o.x = pack2(acc.x, acc.y);
;       o.y = pack2(acc.z, acc.w);
;       *(uint2*)(sU + t * 168 + c4) = o;
;     }
	v_mov_b32_e32 v2, v44
	v_mov_b32_e32 v3, v45
	v_mov_b32_e32 v4, v46
	v_mov_b32_e32 v5, v47
	v_mov_b32_e32 v18, v2
	s_waitcnt vmcnt(8)
	v_mov_b32_e32 v6, v48
	v_mov_b32_e32 v7, v49
	v_mov_b32_e32 v8, v50
	v_mov_b32_e32 v9, v51
	v_mov_b32_e32 v17, v8
	v_mov_b32_e32 v19, v4
	v_mov_b32_e32 v8, v7
	v_mov_b32_e32 v4, v3
	v_mov_b32_e32 v16, v6
	v_pk_fma_f32 v[6:7], v[8:9], v[14:15], v[4:5]
	v_pk_fma_f32 v[12:13], v[16:17], v[12:13], v[18:19]
	v_lshlrev_b32_e32 v9, 16, v81
	v_lshlrev_b32_e32 v8, 16, v80
	s_waitcnt vmcnt(7)
	v_mov_b32_e32 v2, v52
	v_mov_b32_e32 v3, v53
	v_mov_b32_e32 v4, v54
	v_mov_b32_e32 v5, v55
	v_mov_b32_e32 v14, v2
	v_mov_b32_e32 v15, v4
	v_pk_fma_f32 v[8:9], v[14:15], v[8:9], v[12:13]
	v_and_b32_e32 v13, 0xffff0000, v81
	v_and_b32_e32 v12, 0xffff0000, v80
	v_mov_b32_e32 v4, v3
	v_pk_fma_f32 v[6:7], v[4:5], v[12:13], v[6:7]
	v_lshlrev_b32_e32 v13, 16, v83
	v_lshlrev_b32_e32 v12, 16, v82
	s_waitcnt vmcnt(6)
	v_mov_b32_e32 v2, v56
	v_mov_b32_e32 v3, v57
	v_mov_b32_e32 v4, v58
	v_mov_b32_e32 v5, v59
	v_mov_b32_e32 v14, v2
	v_mov_b32_e32 v15, v4
	v_pk_fma_f32 v[8:9], v[14:15], v[12:13], v[8:9]
	v_and_b32_e32 v13, 0xffff0000, v83
	v_and_b32_e32 v12, 0xffff0000, v82
	v_mov_b32_e32 v4, v3
	v_pk_fma_f32 v[6:7], v[4:5], v[12:13], v[6:7]
	v_lshlrev_b32_e32 v11, 16, v85
	v_lshlrev_b32_e32 v10, 16, v84
	v_and_b32_e32 v14, 0xffff0000, v86
	v_and_b32_e32 v15, 0xffff0000, v87
	s_waitcnt vmcnt(5)
	v_mov_b32_e32 v2, v60
	v_mov_b32_e32 v3, v61
	v_mov_b32_e32 v4, v62
	v_mov_b32_e32 v5, v63
	v_mov_b32_e32 v12, v2
	v_mov_b32_e32 v13, v4
	v_pk_fma_f32 v[8:9], v[12:13], v[10:11], v[8:9]
	v_and_b32_e32 v11, 0xffff0000, v85
	v_and_b32_e32 v10, 0xffff0000, v84
	v_mov_b32_e32 v4, v3
	v_pk_fma_f32 v[2:3], v[4:5], v[10:11], v[6:7]
	v_and_b32_sdwa v1, v9, v198 dst_sel:DWORD dst_unused:UNUSED_PAD src0_sel:WORD_1 src1_sel:DWORD
	v_and_b32_sdwa v5, v3, v198 dst_sel:DWORD dst_unused:UNUSED_PAD src0_sel:WORD_1 src1_sel:DWORD
	v_and_b32_sdwa v6, v2, v198 dst_sel:DWORD dst_unused:UNUSED_PAD src0_sel:WORD_1 src1_sel:DWORD
	v_and_b32_sdwa v4, v8, v198 dst_sel:DWORD dst_unused:UNUSED_PAD src0_sel:WORD_1 src1_sel:DWORD
	v_add3_u32 v3, v3, v5, s63
	v_add3_u32 v2, v2, v6, s63
	v_add3_u32 v4, v8, v4, s63
	v_add3_u32 v1, v9, v1, s63
	v_and_b32_e32 v3, 0xffff0000, v3
	v_and_b32_e32 v2, 0xffff0000, v2
	v_or_b32_sdwa v3, v3, v1 dst_sel:DWORD dst_unused:UNUSED_PAD src0_sel:DWORD src1_sel:WORD_1
	v_or_b32_sdwa v2, v2, v4 dst_sel:DWORD dst_unused:UNUSED_PAD src0_sel:DWORD src1_sel:WORD_1
	ds_write_b64 v161, v[2:3]
	v_lshlrev_b64 v[2:3], 2, v[100:101]
	v_lshl_add_u64 v[4:5], s[20:21], 0, v[2:3]
	v_lshl_add_u64 v[2:3], s[22:23], 0, v[2:3]
	v_lshl_add_u64 v[2:3], v[2:3], 0, s[60:61]
	s_nop 0
	v_lshlrev_b64 v[64:65], 2, v[104:105]
	v_lshl_add_u64 v[66:67], s[20:21], 0, v[64:65]
	v_lshl_add_u64 v[64:65], s[22:23], 0, v[64:65]
	v_lshl_add_u64 v[64:65], v[64:65], 0, s[60:61]
	global_load_dwordx4 v[44:47], v[66:67], off
	global_load_dwordx4 v[48:51], v[64:65], off
	v_add_co_u32_e32 v20, vcc, 0x2800, v64
	s_nop 1
	v_addc_co_u32_e32 v21, vcc, 0, v65, vcc
	global_load_dwordx4 v[52:55], v[20:21], off
	v_add_co_u32_e32 v20, vcc, 0x5000, v64
	s_nop 1
	v_addc_co_u32_e32 v21, vcc, 0, v65, vcc
	global_load_dwordx4 v[56:59], v[20:21], off
	v_add_co_u32_e32 v20, vcc, 0x7800, v64
	s_nop 1
	v_addc_co_u32_e32 v21, vcc, 0, v65, vcc
	global_load_dwordx4 v[60:63], v[20:21], off
	v_lshlrev_b32_e32 v12, 16, v86
	v_lshlrev_b32_e32 v13, 16, v87
	s_waitcnt vmcnt(9)
	v_mov_b32_e32 v4, v24
	v_mov_b32_e32 v5, v25
	v_mov_b32_e32 v6, v26
	v_mov_b32_e32 v7, v27
	v_mov_b32_e32 v18, v4
	s_waitcnt vmcnt(8)
	v_mov_b32_e32 v8, v28
	v_mov_b32_e32 v9, v29
	v_mov_b32_e32 v10, v30
	v_mov_b32_e32 v11, v31
	v_mov_b32_e32 v17, v10
	v_mov_b32_e32 v19, v6
	v_mov_b32_e32 v10, v9
	v_mov_b32_e32 v6, v5
	v_mov_b32_e32 v16, v8
	v_pk_fma_f32 v[8:9], v[10:11], v[14:15], v[6:7]
	v_pk_fma_f32 v[12:13], v[16:17], v[12:13], v[18:19]
	v_lshlrev_b32_e32 v11, 16, v89
	v_lshlrev_b32_e32 v10, 16, v88
	s_waitcnt vmcnt(7)
	v_mov_b32_e32 v4, v32
	v_mov_b32_e32 v5, v33
	v_mov_b32_e32 v6, v34
	v_mov_b32_e32 v7, v35
	v_mov_b32_e32 v14, v4
	v_mov_b32_e32 v15, v6
	v_pk_fma_f32 v[10:11], v[14:15], v[10:11], v[12:13]
	v_and_b32_e32 v13, 0xffff0000, v89
	v_and_b32_e32 v12, 0xffff0000, v88
	v_mov_b32_e32 v6, v5
	v_pk_fma_f32 v[8:9], v[6:7], v[12:13], v[8:9]
	v_lshlrev_b32_e32 v13, 16, v91
	s_nop 0
	v_lshlrev_b32_e32 v12, 16, v90
	s_waitcnt vmcnt(6)
	v_mov_b32_e32 v4, v36
	v_mov_b32_e32 v5, v37
	v_mov_b32_e32 v6, v38
	v_mov_b32_e32 v7, v39
	v_mov_b32_e32 v14, v4
	v_mov_b32_e32 v15, v6
	v_mov_b32_e32 v6, v5
	v_pk_fma_f32 v[10:11], v[14:15], v[12:13], v[10:11]
	v_and_b32_e32 v13, 0xffff0000, v91
	v_and_b32_e32 v12, 0xffff0000, v90
	v_pk_fma_f32 v[6:7], v[6:7], v[12:13], v[8:9]
	v_lshlrev_b32_e32 v9, 16, v93
	v_lshlrev_b32_e32 v8, 16, v92
	v_and_b32_e32 v14, 0xffff0000, v102
	v_and_b32_e32 v15, 0xffff0000, v103
	s_waitcnt vmcnt(5)
; __device__ __forceinline__ float bflo(unsigned v) { return __uint_as_float(v << 16); }
; __device__ __forceinline__ float bfhi(unsigned v) { return __uint_as_float(v & 0xffff0000u); }
; __device__ __forceinline__ unsigned pack2(float a, float b) { return (unsigned)f2bf(a) | ((unsigned)f2bf(b) << 16); }
; __device__ void odd_tiles(int tid_, int bid_, int nblk_, const Params& p, int oi, int mode, bool skip_ctx, char* smem) {
;     ...
; #pragma unroll
;     for (int i = 0; i < 5; ++i) {
;       int e = tid + i * 256, t = e / 40, c4 = (e % 40) * 4;
;       float4 acc = *(const float4*)(p.od_conv_b + oi * DC + cb + c4);
; #pragma unroll
;       for (int j = 0; j < 4; ++j) {
;         uint2 xv = xr[i][j];
;         float4 wv = *(const float4*)(p.od_conv_w + ((size_t)oi * 4 + j) * DC + cb + c4);
;         acc.x += bflo(xv.x) * wv.x; acc.y += bfhi(xv.x) * wv.y; acc.z += bflo(xv.y) * wv.z; acc.w += bfhi(xv.y) * wv.w;
;       }
;       uint2 o;
;       o.x = pack2(acc.x, acc.y);
;       o.y = pack2(acc.z, acc.w);
;       *(uint2*)(sU + t * 168 + c4) = o;
;     }
	v_mov_b32_e32 v2, v40
	v_mov_b32_e32 v3, v41
	v_mov_b32_e32 v4, v42
	v_mov_b32_e32 v5, v43
	v_mov_b32_e32 v12, v2
	v_mov_b32_e32 v13, v4
	v_pk_fma_f32 v[8:9], v[12:13], v[8:9], v[10:11]
	v_and_b32_e32 v11, 0xffff0000, v93
	v_and_b32_e32 v10, 0xffff0000, v92
	v_mov_b32_e32 v4, v3
	v_pk_fma_f32 v[2:3], v[4:5], v[10:11], v[6:7]
	v_and_b32_sdwa v1, v9, v198 dst_sel:DWORD dst_unused:UNUSED_PAD src0_sel:WORD_1 src1_sel:DWORD
	v_and_b32_sdwa v5, v3, v198 dst_sel:DWORD dst_unused:UNUSED_PAD src0_sel:WORD_1 src1_sel:DWORD
	v_and_b32_sdwa v6, v2, v198 dst_sel:DWORD dst_unused:UNUSED_PAD src0_sel:WORD_1 src1_sel:DWORD
	v_and_b32_sdwa v4, v8, v198 dst_sel:DWORD dst_unused:UNUSED_PAD src0_sel:WORD_1 src1_sel:DWORD
	v_add3_u32 v3, v3, v5, s63
	v_add3_u32 v2, v2, v6, s63
	v_add3_u32 v4, v8, v4, s63
	v_add3_u32 v1, v9, v1, s63
	v_and_b32_e32 v3, 0xffff0000, v3
	v_and_b32_e32 v2, 0xffff0000, v2
	v_or_b32_sdwa v3, v3, v1 dst_sel:DWORD dst_unused:UNUSED_PAD src0_sel:DWORD src1_sel:WORD_1
	v_or_b32_sdwa v2, v2, v4 dst_sel:DWORD dst_unused:UNUSED_PAD src0_sel:DWORD src1_sel:WORD_1
	ds_write_b64 v180, v[2:3]
	v_lshlrev_b64 v[2:3], 2, v[104:105]
	v_lshl_add_u64 v[4:5], s[20:21], 0, v[2:3]
	v_lshl_add_u64 v[2:3], s[22:23], 0, v[2:3]
	v_lshl_add_u64 v[10:11], v[2:3], 0, s[60:61]
	s_nop 0
	v_lshlrev_b64 v[64:65], 2, v[106:107]
	v_lshl_add_u64 v[66:67], s[20:21], 0, v[64:65]
	v_lshl_add_u64 v[64:65], s[22:23], 0, v[64:65]
	v_lshl_add_u64 v[64:65], v[64:65], 0, s[60:61]
	global_load_dwordx4 v[24:27], v[66:67], off
	global_load_dwordx4 v[28:31], v[64:65], off
	v_add_co_u32_e32 v20, vcc, 0x2800, v64
	s_nop 1
	v_addc_co_u32_e32 v21, vcc, 0, v65, vcc
	global_load_dwordx4 v[32:35], v[20:21], off
	v_add_co_u32_e32 v20, vcc, 0x5000, v64
	s_nop 1
	v_addc_co_u32_e32 v21, vcc, 0, v65, vcc
	global_load_dwordx4 v[36:39], v[20:21], off
	v_add_co_u32_e32 v20, vcc, 0x7800, v64
	s_nop 1
	v_addc_co_u32_e32 v21, vcc, 0, v65, vcc
	global_load_dwordx4 v[40:43], v[20:21], off
	v_lshlrev_b32_e32 v12, 16, v102
	v_lshlrev_b32_e32 v13, 16, v103
	s_waitcnt vmcnt(9)
	v_mov_b32_e32 v2, v44
	v_mov_b32_e32 v3, v45
	v_mov_b32_e32 v4, v46
	v_mov_b32_e32 v5, v47
	v_mov_b32_e32 v18, v2
	s_waitcnt vmcnt(8)
	v_mov_b32_e32 v6, v48
	v_mov_b32_e32 v7, v49
	v_mov_b32_e32 v8, v50
	v_mov_b32_e32 v9, v51
	v_mov_b32_e32 v17, v8
	v_mov_b32_e32 v19, v4
	v_mov_b32_e32 v8, v7
	v_mov_b32_e32 v4, v3
	v_mov_b32_e32 v16, v6
	v_pk_fma_f32 v[6:7], v[8:9], v[14:15], v[4:5]
	v_pk_fma_f32 v[12:13], v[16:17], v[12:13], v[18:19]
	v_lshlrev_b32_e32 v9, 16, v109
	v_lshlrev_b32_e32 v8, 16, v108
	s_waitcnt vmcnt(7)
	v_mov_b32_e32 v2, v52
	v_mov_b32_e32 v3, v53
	v_mov_b32_e32 v4, v54
	v_mov_b32_e32 v5, v55
	v_mov_b32_e32 v14, v2
	v_mov_b32_e32 v15, v4
	v_pk_fma_f32 v[8:9], v[14:15], v[8:9], v[12:13]
	v_and_b32_e32 v13, 0xffff0000, v109
	v_and_b32_e32 v12, 0xffff0000, v108
	v_mov_b32_e32 v4, v3
	v_pk_fma_f32 v[6:7], v[4:5], v[12:13], v[6:7]
	v_lshlrev_b32_e32 v13, 16, v127
	v_lshlrev_b32_e32 v12, 16, v126
	s_waitcnt vmcnt(6)
	v_mov_b32_e32 v2, v56
	v_mov_b32_e32 v3, v57
	v_mov_b32_e32 v4, v58
	v_mov_b32_e32 v5, v59
	v_mov_b32_e32 v14, v2
	v_mov_b32_e32 v15, v4
	v_pk_fma_f32 v[8:9], v[14:15], v[12:13], v[8:9]
	v_and_b32_e32 v13, 0xffff0000, v127
	v_and_b32_e32 v12, 0xffff0000, v126
	v_mov_b32_e32 v4, v3
	v_pk_fma_f32 v[6:7], v[4:5], v[12:13], v[6:7]
	v_lshlrev_b32_e32 v11, 16, v133
	v_lshlrev_b32_e32 v10, 16, v132
	v_and_b32_e32 v14, 0xffff0000, v140
	v_and_b32_e32 v15, 0xffff0000, v141
	s_waitcnt vmcnt(5)
; __device__ __forceinline__ float bflo(unsigned v) { return __uint_as_float(v << 16); }
; __device__ __forceinline__ float bfhi(unsigned v) { return __uint_as_float(v & 0xffff0000u); }
; __device__ __forceinline__ unsigned pack2(float a, float b) { return (unsigned)f2bf(a) | ((unsigned)f2bf(b) << 16); }
; __device__ void odd_tiles(int tid_, int bid_, int nblk_, const Params& p, int oi, int mode, bool skip_ctx, char* smem) {
;     ...
; #pragma unroll
;     for (int i = 0; i < 5; ++i) {
;       int e = tid + i * 256, t = e / 40, c4 = (e % 40) * 4;
;       float4 acc = *(const float4*)(p.od_conv_b + oi * DC + cb + c4);
; #pragma unroll
;       for (int j = 0; j < 4; ++j) {
;         uint2 xv = xr[i][j];
;         float4 wv = *(const float4*)(p.od_conv_w + ((size_t)oi * 4 + j) * DC + cb + c4);
;         acc.x += bflo(xv.x) * wv.x; acc.y += bfhi(xv.x) * wv.y; acc.z += bflo(xv.y) * wv.z; acc.w += bfhi(xv.y) * wv.w;
;       }
;       uint2 o;
;       o.x = pack2(acc.x, acc.y);
;       o.y = pack2(acc.z, acc.w);
;       *(uint2*)(sU + t * 168 + c4) = o;
;     }
	v_mov_b32_e32 v2, v60
	v_mov_b32_e32 v3, v61
	v_mov_b32_e32 v4, v62
	v_mov_b32_e32 v5, v63
	v_mov_b32_e32 v12, v2
	v_mov_b32_e32 v13, v4
	v_pk_fma_f32 v[8:9], v[12:13], v[10:11], v[8:9]
	v_and_b32_e32 v11, 0xffff0000, v133
	v_and_b32_e32 v10, 0xffff0000, v132
	v_mov_b32_e32 v4, v3
	v_pk_fma_f32 v[2:3], v[4:5], v[10:11], v[6:7]
	v_and_b32_sdwa v1, v9, v198 dst_sel:DWORD dst_unused:UNUSED_PAD src0_sel:WORD_1 src1_sel:DWORD
	v_and_b32_sdwa v5, v3, v198 dst_sel:DWORD dst_unused:UNUSED_PAD src0_sel:WORD_1 src1_sel:DWORD
	v_and_b32_sdwa v6, v2, v198 dst_sel:DWORD dst_unused:UNUSED_PAD src0_sel:WORD_1 src1_sel:DWORD
	v_and_b32_sdwa v4, v8, v198 dst_sel:DWORD dst_unused:UNUSED_PAD src0_sel:WORD_1 src1_sel:DWORD
	v_add3_u32 v3, v3, v5, s63
	v_add3_u32 v2, v2, v6, s63
	v_add3_u32 v4, v8, v4, s63
	v_add3_u32 v1, v9, v1, s63
	v_and_b32_e32 v3, 0xffff0000, v3
	v_and_b32_e32 v2, 0xffff0000, v2
	v_or_b32_sdwa v3, v3, v1 dst_sel:DWORD dst_unused:UNUSED_PAD src0_sel:DWORD src1_sel:WORD_1
	v_or_b32_sdwa v2, v2, v4 dst_sel:DWORD dst_unused:UNUSED_PAD src0_sel:DWORD src1_sel:WORD_1
	ds_write_b64 v182, v[2:3]
	v_lshlrev_b64 v[2:3], 2, v[106:107]
	v_lshl_add_u64 v[4:5], s[20:21], 0, v[2:3]
	v_lshl_add_u64 v[2:3], s[22:23], 0, v[2:3]
	v_lshl_add_u64 v[10:11], v[2:3], 0, s[60:61]
	s_nop 0
	v_lshlrev_b32_e32 v12, 16, v140
	v_lshlrev_b32_e32 v13, 16, v141
	s_waitcnt vmcnt(4)
	v_mov_b32_e32 v2, v24
	v_mov_b32_e32 v3, v25
	v_mov_b32_e32 v4, v26
	v_mov_b32_e32 v5, v27
	v_mov_b32_e32 v18, v2
	s_waitcnt vmcnt(3)
	v_mov_b32_e32 v6, v28
	v_mov_b32_e32 v7, v29
	v_mov_b32_e32 v8, v30
	v_mov_b32_e32 v9, v31
	v_mov_b32_e32 v17, v8
	v_mov_b32_e32 v19, v4
	v_mov_b32_e32 v8, v7
	v_mov_b32_e32 v4, v3
	v_mov_b32_e32 v16, v6
	v_pk_fma_f32 v[6:7], v[8:9], v[14:15], v[4:5]
	v_pk_fma_f32 v[12:13], v[16:17], v[12:13], v[18:19]
	v_lshlrev_b32_e32 v9, 16, v143
	v_lshlrev_b32_e32 v8, 16, v142
	s_waitcnt vmcnt(2)
	v_mov_b32_e32 v2, v32
	v_mov_b32_e32 v3, v33
	v_mov_b32_e32 v4, v34
	v_mov_b32_e32 v5, v35
	v_mov_b32_e32 v14, v2
	v_mov_b32_e32 v15, v4
	v_pk_fma_f32 v[12:13], v[14:15], v[8:9], v[12:13]
	v_and_b32_e32 v9, 0xffff0000, v143
	v_and_b32_e32 v8, 0xffff0000, v142
	v_mov_b32_e32 v4, v3
	v_pk_fma_f32 v[2:3], v[4:5], v[8:9], v[6:7]
	s_nop 1
	v_lshlrev_b32_e32 v5, 16, v145
	v_lshlrev_b32_e32 v4, 16, v144
	s_waitcnt vmcnt(1)
	v_mov_b32_e32 v6, v36
	v_mov_b32_e32 v7, v37
	v_mov_b32_e32 v8, v38
	v_mov_b32_e32 v9, v39
	v_mov_b32_e32 v14, v6
	v_mov_b32_e32 v15, v8
	v_pk_fma_f32 v[4:5], v[14:15], v[4:5], v[12:13]
	v_and_b32_e32 v13, 0xffff0000, v145
	v_and_b32_e32 v12, 0xffff0000, v144
	v_mov_b32_e32 v8, v7
	v_pk_fma_f32 v[2:3], v[8:9], v[12:13], v[2:3]
	v_lshlrev_b32_e32 v11, 16, v147
	v_lshlrev_b32_e32 v10, 16, v146
	s_waitcnt vmcnt(0)
	v_mov_b32_e32 v6, v40
	v_mov_b32_e32 v7, v41
	v_mov_b32_e32 v8, v42
	v_mov_b32_e32 v9, v43
	v_mov_b32_e32 v12, v6
	v_mov_b32_e32 v13, v8
	v_pk_fma_f32 v[4:5], v[12:13], v[10:11], v[4:5]
	v_and_b32_e32 v11, 0xffff0000, v147
	v_and_b32_e32 v10, 0xffff0000, v146
	v_mov_b32_e32 v8, v7
	v_pk_fma_f32 v[2:3], v[8:9], v[10:11], v[2:3]
	v_and_b32_sdwa v1, v5, v198 dst_sel:DWORD dst_unused:UNUSED_PAD src0_sel:WORD_1 src1_sel:DWORD
	v_and_b32_sdwa v6, v4, v198 dst_sel:DWORD dst_unused:UNUSED_PAD src0_sel:WORD_1 src1_sel:DWORD
	v_add3_u32 v4, v4, v6, s63
	v_add3_u32 v1, v5, v1, s63
	v_and_b32_sdwa v5, v3, v198 dst_sel:DWORD dst_unused:UNUSED_PAD src0_sel:WORD_1 src1_sel:DWORD
	v_and_b32_sdwa v6, v2, v198 dst_sel:DWORD dst_unused:UNUSED_PAD src0_sel:WORD_1 src1_sel:DWORD
	v_add3_u32 v3, v3, v5, s63
	v_add3_u32 v2, v2, v6, s63
	v_and_b32_e32 v3, 0xffff0000, v3
	v_and_b32_e32 v2, 0xffff0000, v2
	v_or_b32_sdwa v3, v3, v1 dst_sel:DWORD dst_unused:UNUSED_PAD src0_sel:DWORD src1_sel:WORD_1
	v_or_b32_sdwa v2, v2, v4 dst_sel:DWORD dst_unused:UNUSED_PAD src0_sel:DWORD src1_sel:WORD_1
	ds_write_b64 v184, v[2:3]
	s_waitcnt lgkmcnt(0)
	s_barrier
	s_branch .LBB0_102

; __device__ __forceinline__ float bflo(unsigned v) { return __uint_as_float(v << 16); }
; __device__ __forceinline__ float bfhi(unsigned v) { return __uint_as_float(v & 0xffff0000u); }
; __device__ __forceinline__ unsigned pack2(float a, float b) { return (unsigned)f2bf(a) | ((unsigned)f2bf(b) << 16); }
; __device__ void odd_tiles(int tid_, int bid_, int nblk_, const Params& p, int oi, int mode, bool skip_ctx, char* smem) {
;     ...
; #pragma unroll
;     for (int i = 0; i < 5; ++i) {
;       int e = tid + i * 256, t = e / 40, c4 = (e % 40) * 4;
;       float4 acc = *(const float4*)(p.od_conv_b + oi * DC + cb + c4);
; #pragma unroll
;       for (int j = 0; j < 4; ++j) {
;         uint2 xv = xr[i][j];
;         float4 wv = *(const float4*)(p.od_conv_w + ((size_t)oi * 4 + j) * DC + cb + c4);
;         acc.x += bflo(xv.x) * wv.x; acc.y += bfhi(xv.x) * wv.y; acc.z += bflo(xv.y) * wv.z; acc.w += bfhi(xv.y) * wv.w;
;       }
;       uint2 o;
;       o.x = pack2(acc.x, acc.y);
;       o.y = pack2(acc.z, acc.w);
;       *(uint2*)(sU + t * 168 + c4) = o;
;     }
.LBB0_229:
	s_and_b32 s28, s27, 15
	s_mul_i32 s0, s28, 0xa0
	s_lshl_b32 s22, s0, 2
	s_add_u32 s20, s25, s22
	v_readlane_b32 s64, v252, 33
	s_addc_u32 s21, s26, 0
	v_readlane_b32 s76, v252, 45
	v_readlane_b32 s77, v252, 46
	s_add_u32 s22, s76, s22
	v_lshlrev_b64 v[2:3], 2, v[98:99]
	s_addc_u32 s23, s77, 0
	v_lshl_add_u64 v[4:5], s[20:21], 0, v[2:3]
	v_lshl_add_u64 v[2:3], s[22:23], 0, v[2:3]
	s_mov_b32 s61, s1
	v_lshl_add_u64 v[10:11], v[2:3], 0, s[60:61]
	global_load_dwordx4 v[24:27], v[4:5], off
	s_nop 0
	global_load_dwordx4 v[28:31], v[10:11], off
	v_add_co_u32_e32 v20, vcc, 0x2800, v10
	s_nop 1
	v_addc_co_u32_e32 v21, vcc, 0, v11, vcc
	global_load_dwordx4 v[32:35], v[20:21], off
	v_add_co_u32_e32 v20, vcc, 0x5000, v10
	s_nop 1
	v_addc_co_u32_e32 v21, vcc, 0, v11, vcc
	global_load_dwordx4 v[36:39], v[20:21], off
	v_add_co_u32_e32 v20, vcc, 0x7800, v10
	s_nop 1
	v_addc_co_u32_e32 v21, vcc, 0, v11, vcc
	global_load_dwordx4 v[40:43], v[20:21], off
	v_lshlrev_b64 v[64:65], 2, v[100:101]
	v_lshl_add_u64 v[66:67], s[20:21], 0, v[64:65]
	v_lshl_add_u64 v[64:65], s[22:23], 0, v[64:65]
	v_lshl_add_u64 v[64:65], v[64:65], 0, s[60:61]
	global_load_dwordx4 v[44:47], v[66:67], off
	global_load_dwordx4 v[48:51], v[64:65], off
	v_add_co_u32_e32 v20, vcc, 0x2800, v64
	s_nop 1
	v_addc_co_u32_e32 v21, vcc, 0, v65, vcc
	global_load_dwordx4 v[52:55], v[20:21], off
	v_add_co_u32_e32 v20, vcc, 0x5000, v64
	s_nop 1
	v_addc_co_u32_e32 v21, vcc, 0, v65, vcc
	global_load_dwordx4 v[56:59], v[20:21], off
	v_add_co_u32_e32 v20, vcc, 0x7800, v64
	s_nop 1
	v_addc_co_u32_e32 v21, vcc, 0, v65, vcc
	global_load_dwordx4 v[60:63], v[20:21], off
	s_movk_i32 s34, 0x2000
	v_and_b32_e32 v14, 0xffff0000, v70
	v_and_b32_e32 v15, 0xffff0000, v71
	v_lshlrev_b32_e32 v12, 16, v70
	v_lshlrev_b32_e32 v13, 16, v71
	s_movk_i32 s35, 0x5000
	s_movk_i32 s36, 0x7000
	s_movk_i32 s2, 0x2000
	v_readlane_b32 s65, v252, 34
	v_readlane_b32 s66, v252, 35
	v_readlane_b32 s67, v252, 36
	v_readlane_b32 s68, v252, 37
	v_readlane_b32 s69, v252, 38
	v_readlane_b32 s70, v252, 39
	v_readlane_b32 s71, v252, 40
	v_readlane_b32 s72, v252, 41
	v_readlane_b32 s73, v252, 42
	v_readlane_b32 s74, v252, 43
	v_readlane_b32 s75, v252, 44
	v_readlane_b32 s78, v252, 47
	v_readlane_b32 s79, v252, 48
	s_waitcnt vmcnt(9)
	v_mov_b32_e32 v2, v24
	v_mov_b32_e32 v3, v25
	v_mov_b32_e32 v4, v26
	v_mov_b32_e32 v5, v27
	v_mov_b32_e32 v18, v2
	s_waitcnt vmcnt(8)
	v_mov_b32_e32 v6, v28
	v_mov_b32_e32 v7, v29
	v_mov_b32_e32 v8, v30
	v_mov_b32_e32 v9, v31
	v_mov_b32_e32 v17, v8
	v_mov_b32_e32 v19, v4
	v_mov_b32_e32 v8, v7
	v_mov_b32_e32 v4, v3
	v_mov_b32_e32 v16, v6
	v_pk_fma_f32 v[6:7], v[8:9], v[14:15], v[4:5]
	v_pk_fma_f32 v[12:13], v[16:17], v[12:13], v[18:19]
	v_lshlrev_b32_e32 v9, 16, v73
	v_lshlrev_b32_e32 v8, 16, v72
	s_waitcnt vmcnt(7)
	v_mov_b32_e32 v2, v32
	v_mov_b32_e32 v3, v33
	v_mov_b32_e32 v4, v34
	v_mov_b32_e32 v5, v35
	v_mov_b32_e32 v14, v2
	v_mov_b32_e32 v15, v4
	v_pk_fma_f32 v[8:9], v[14:15], v[8:9], v[12:13]
	v_and_b32_e32 v13, 0xffff0000, v73
	v_and_b32_e32 v12, 0xffff0000, v72
	v_mov_b32_e32 v4, v3
	v_pk_fma_f32 v[6:7], v[4:5], v[12:13], v[6:7]
	v_lshlrev_b32_e32 v13, 16, v75
	v_lshlrev_b32_e32 v12, 16, v74
	s_waitcnt vmcnt(6)
	v_mov_b32_e32 v2, v36
	v_mov_b32_e32 v3, v37
	v_mov_b32_e32 v4, v38
	v_mov_b32_e32 v5, v39
	v_mov_b32_e32 v14, v2
	v_mov_b32_e32 v15, v4
	v_pk_fma_f32 v[8:9], v[14:15], v[12:13], v[8:9]
	v_and_b32_e32 v13, 0xffff0000, v75
	v_and_b32_e32 v12, 0xffff0000, v74
	v_mov_b32_e32 v4, v3
	v_pk_fma_f32 v[6:7], v[4:5], v[12:13], v[6:7]
	v_lshlrev_b32_e32 v11, 16, v77
	v_lshlrev_b32_e32 v10, 16, v76
	v_and_b32_e32 v14, 0xffff0000, v78
	v_and_b32_e32 v15, 0xffff0000, v79
	s_waitcnt vmcnt(5)
	v_mov_b32_e32 v2, v40
	v_mov_b32_e32 v3, v41
	v_mov_b32_e32 v4, v42
	v_mov_b32_e32 v5, v43
	v_mov_b32_e32 v12, v2
	v_mov_b32_e32 v13, v4
	v_pk_fma_f32 v[8:9], v[12:13], v[10:11], v[8:9]
	v_and_b32_e32 v11, 0xffff0000, v77
	v_and_b32_e32 v10, 0xffff0000, v76
	v_mov_b32_e32 v4, v3
	v_pk_fma_f32 v[2:3], v[4:5], v[10:11], v[6:7]
	v_and_b32_sdwa v1, v9, v198 dst_sel:DWORD dst_unused:UNUSED_PAD src0_sel:WORD_1 src1_sel:DWORD
	v_and_b32_sdwa v5, v3, v198 dst_sel:DWORD dst_unused:UNUSED_PAD src0_sel:WORD_1 src1_sel:DWORD
	v_and_b32_sdwa v6, v2, v198 dst_sel:DWORD dst_unused:UNUSED_PAD src0_sel:WORD_1 src1_sel:DWORD
	v_and_b32_sdwa v4, v8, v198 dst_sel:DWORD dst_unused:UNUSED_PAD src0_sel:WORD_1 src1_sel:DWORD
	v_add3_u32 v3, v3, v5, s63
	v_add3_u32 v2, v2, v6, s63
	v_add3_u32 v4, v8, v4, s63
	v_add3_u32 v1, v9, v1, s63
	v_and_b32_e32 v3, 0xffff0000, v3
	v_and_b32_e32 v2, 0xffff0000, v2
	v_or_b32_sdwa v3, v3, v1 dst_sel:DWORD dst_unused:UNUSED_PAD src0_sel:DWORD src1_sel:WORD_1
	v_or_b32_sdwa v2, v2, v4 dst_sel:DWORD dst_unused:UNUSED_PAD src0_sel:DWORD src1_sel:WORD_1
	ds_write_b64 v167, v[2:3]
	v_lshlrev_b64 v[2:3], 2, v[100:101]
	v_lshl_add_u64 v[4:5], s[20:21], 0, v[2:3]
	v_lshl_add_u64 v[2:3], s[22:23], 0, v[2:3]
	v_lshl_add_u64 v[10:11], v[2:3], 0, s[60:61]
	s_nop 0
	v_lshlrev_b64 v[64:65], 2, v[102:103]
	v_lshl_add_u64 v[66:67], s[20:21], 0, v[64:65]
	v_lshl_add_u64 v[64:65], s[22:23], 0, v[64:65]
	v_lshl_add_u64 v[64:65], v[64:65], 0, s[60:61]
	global_load_dwordx4 v[24:27], v[66:67], off
	global_load_dwordx4 v[28:31], v[64:65], off
	v_add_co_u32_e32 v20, vcc, 0x2800, v64
	s_nop 1
	v_addc_co_u32_e32 v21, vcc, 0, v65, vcc
	global_load_dwordx4 v[32:35], v[20:21], off
	v_add_co_u32_e32 v20, vcc, 0x5000, v64
	s_nop 1
	v_addc_co_u32_e32 v21, vcc, 0, v65, vcc
	global_load_dwordx4 v[36:39], v[20:21], off
	v_add_co_u32_e32 v20, vcc, 0x7800, v64
	s_nop 1
	v_addc_co_u32_e32 v21, vcc, 0, v65, vcc
	global_load_dwordx4 v[40:43], v[20:21], off
	v_lshlrev_b32_e32 v12, 16, v78
	v_lshlrev_b32_e32 v13, 16, v79
	s_waitcnt vmcnt(9)
; __device__ __forceinline__ float bflo(unsigned v) { return __uint_as_float(v << 16); }
; __device__ __forceinline__ float bfhi(unsigned v) { return __uint_as_float(v & 0xffff0000u); }
; __device__ __forceinline__ unsigned pack2(float a, float b) { return (unsigned)f2bf(a) | ((unsigned)f2bf(b) << 16); }
; __device__ void odd_tiles(int tid_, int bid_, int nblk_, const Params& p, int oi, int mode, bool skip_ctx, char* smem) {
;     ...
; #pragma unroll
;     for (int i = 0; i < 5; ++i) {
;       int e = tid + i * 256, t = e / 40, c4 = (e % 40) * 4;
;       float4 acc = *(const float4*)(p.od_conv_b + oi * DC + cb + c4);
; #pragma unroll
;       for (int j = 0; j < 4; ++j) {
;         uint2 xv = xr[i][j];
;         float4 wv = *(const float4*)(p.od_conv_w + ((size_t)oi * 4 + j) * DC + cb + c4);
;         acc.x += bflo(xv.x) * wv.x; acc.y += bfhi(xv.x) * wv.y; acc.z += bflo(xv.y) * wv.z; acc.w += bfhi(xv.y) * wv.w;
;       }
;       uint2 o;
;       o.x = pack2(acc.x, acc.y);
;       o.y = pack2(acc.z, acc.w);
;       *(uint2*)(sU + t * 168 + c4) = o;
;     }
	v_mov_b32_e32 v2, v44
	v_mov_b32_e32 v3, v45
	v_mov_b32_e32 v4, v46
	v_mov_b32_e32 v5, v47
	v_mov_b32_e32 v18, v2
	s_waitcnt vmcnt(8)
	v_mov_b32_e32 v6, v48
	v_mov_b32_e32 v7, v49
	v_mov_b32_e32 v8, v50
	v_mov_b32_e32 v9, v51
	v_mov_b32_e32 v17, v8
	v_mov_b32_e32 v19, v4
	v_mov_b32_e32 v8, v7
	v_mov_b32_e32 v4, v3
	v_mov_b32_e32 v16, v6
	v_pk_fma_f32 v[6:7], v[8:9], v[14:15], v[4:5]
	v_pk_fma_f32 v[12:13], v[16:17], v[12:13], v[18:19]
	v_lshlrev_b32_e32 v9, 16, v81
	v_lshlrev_b32_e32 v8, 16, v80
	s_waitcnt vmcnt(7)
	v_mov_b32_e32 v2, v52
	v_mov_b32_e32 v3, v53
	v_mov_b32_e32 v4, v54
	v_mov_b32_e32 v5, v55
	v_mov_b32_e32 v14, v2
	v_mov_b32_e32 v15, v4
	v_pk_fma_f32 v[8:9], v[14:15], v[8:9], v[12:13]
	v_and_b32_e32 v13, 0xffff0000, v81
	v_and_b32_e32 v12, 0xffff0000, v80
	v_mov_b32_e32 v4, v3
	v_pk_fma_f32 v[6:7], v[4:5], v[12:13], v[6:7]
	v_lshlrev_b32_e32 v13, 16, v83
	v_lshlrev_b32_e32 v12, 16, v82
	s_waitcnt vmcnt(6)
	v_mov_b32_e32 v2, v56
	v_mov_b32_e32 v3, v57
	v_mov_b32_e32 v4, v58
	v_mov_b32_e32 v5, v59
	v_mov_b32_e32 v14, v2
	v_mov_b32_e32 v15, v4
	v_pk_fma_f32 v[8:9], v[14:15], v[12:13], v[8:9]
	v_and_b32_e32 v13, 0xffff0000, v83
	v_and_b32_e32 v12, 0xffff0000, v82
	v_mov_b32_e32 v4, v3
	v_pk_fma_f32 v[6:7], v[4:5], v[12:13], v[6:7]
	v_lshlrev_b32_e32 v11, 16, v85
	v_lshlrev_b32_e32 v10, 16, v84
	v_and_b32_e32 v14, 0xffff0000, v86
	v_and_b32_e32 v15, 0xffff0000, v87
	s_waitcnt vmcnt(5)
	v_mov_b32_e32 v2, v60
	v_mov_b32_e32 v3, v61
	v_mov_b32_e32 v4, v62
	v_mov_b32_e32 v5, v63
	v_mov_b32_e32 v12, v2
	v_mov_b32_e32 v13, v4
	v_pk_fma_f32 v[8:9], v[12:13], v[10:11], v[8:9]
	v_and_b32_e32 v11, 0xffff0000, v85
	v_and_b32_e32 v10, 0xffff0000, v84
	v_mov_b32_e32 v4, v3
	v_pk_fma_f32 v[2:3], v[4:5], v[10:11], v[6:7]
	v_and_b32_sdwa v1, v9, v198 dst_sel:DWORD dst_unused:UNUSED_PAD src0_sel:WORD_1 src1_sel:DWORD
	v_and_b32_sdwa v5, v3, v198 dst_sel:DWORD dst_unused:UNUSED_PAD src0_sel:WORD_1 src1_sel:DWORD
	v_and_b32_sdwa v6, v2, v198 dst_sel:DWORD dst_unused:UNUSED_PAD src0_sel:WORD_1 src1_sel:DWORD
	v_and_b32_sdwa v4, v8, v198 dst_sel:DWORD dst_unused:UNUSED_PAD src0_sel:WORD_1 src1_sel:DWORD
	v_add3_u32 v3, v3, v5, s63
	v_add3_u32 v2, v2, v6, s63
	v_add3_u32 v4, v8, v4, s63
	v_add3_u32 v1, v9, v1, s63
	v_and_b32_e32 v3, 0xffff0000, v3
	v_and_b32_e32 v2, 0xffff0000, v2
	v_or_b32_sdwa v3, v3, v1 dst_sel:DWORD dst_unused:UNUSED_PAD src0_sel:DWORD src1_sel:WORD_1
	v_or_b32_sdwa v2, v2, v4 dst_sel:DWORD dst_unused:UNUSED_PAD src0_sel:DWORD src1_sel:WORD_1
	ds_write_b64 v169, v[2:3]
	v_lshlrev_b64 v[2:3], 2, v[102:103]
	v_lshl_add_u64 v[4:5], s[20:21], 0, v[2:3]
	v_lshl_add_u64 v[2:3], s[22:23], 0, v[2:3]
	v_lshl_add_u64 v[2:3], v[2:3], 0, s[60:61]
	s_nop 0
	v_lshlrev_b64 v[64:65], 2, v[106:107]
	v_lshl_add_u64 v[66:67], s[20:21], 0, v[64:65]
	v_lshl_add_u64 v[64:65], s[22:23], 0, v[64:65]
	v_lshl_add_u64 v[64:65], v[64:65], 0, s[60:61]
	global_load_dwordx4 v[44:47], v[66:67], off
	global_load_dwordx4 v[48:51], v[64:65], off
	v_add_co_u32_e32 v20, vcc, 0x2800, v64
	s_nop 1
	v_addc_co_u32_e32 v21, vcc, 0, v65, vcc
	global_load_dwordx4 v[52:55], v[20:21], off
	v_add_co_u32_e32 v20, vcc, 0x5000, v64
	s_nop 1
	v_addc_co_u32_e32 v21, vcc, 0, v65, vcc
	global_load_dwordx4 v[56:59], v[20:21], off
	v_add_co_u32_e32 v20, vcc, 0x7800, v64
	s_nop 1
	v_addc_co_u32_e32 v21, vcc, 0, v65, vcc
	global_load_dwordx4 v[60:63], v[20:21], off
	v_lshlrev_b32_e32 v12, 16, v86
	v_lshlrev_b32_e32 v13, 16, v87
	s_waitcnt vmcnt(9)
	v_mov_b32_e32 v4, v24
	v_mov_b32_e32 v5, v25
	v_mov_b32_e32 v6, v26
	v_mov_b32_e32 v7, v27
	v_mov_b32_e32 v18, v4
	s_waitcnt vmcnt(8)
	v_mov_b32_e32 v8, v28
	v_mov_b32_e32 v9, v29
	v_mov_b32_e32 v10, v30
	v_mov_b32_e32 v11, v31
	v_mov_b32_e32 v17, v10
	v_mov_b32_e32 v19, v6
	v_mov_b32_e32 v10, v9
	v_mov_b32_e32 v6, v5
	v_mov_b32_e32 v16, v8
	v_pk_fma_f32 v[8:9], v[10:11], v[14:15], v[6:7]
	v_pk_fma_f32 v[12:13], v[16:17], v[12:13], v[18:19]
	v_lshlrev_b32_e32 v11, 16, v89
	v_lshlrev_b32_e32 v10, 16, v88
	s_waitcnt vmcnt(7)
	v_mov_b32_e32 v4, v32
	v_mov_b32_e32 v5, v33
	v_mov_b32_e32 v6, v34
	v_mov_b32_e32 v7, v35
	v_mov_b32_e32 v14, v4
	v_mov_b32_e32 v15, v6
	v_pk_fma_f32 v[10:11], v[14:15], v[10:11], v[12:13]
	v_and_b32_e32 v13, 0xffff0000, v89
	v_and_b32_e32 v12, 0xffff0000, v88
	v_mov_b32_e32 v6, v5
	v_pk_fma_f32 v[8:9], v[6:7], v[12:13], v[8:9]
	v_lshlrev_b32_e32 v13, 16, v91
	s_nop 0
	v_lshlrev_b32_e32 v12, 16, v90
	s_waitcnt vmcnt(6)
	v_mov_b32_e32 v4, v36
	v_mov_b32_e32 v5, v37
	v_mov_b32_e32 v6, v38
	v_mov_b32_e32 v7, v39
	v_mov_b32_e32 v14, v4
	v_mov_b32_e32 v15, v6
	v_mov_b32_e32 v6, v5
	v_pk_fma_f32 v[10:11], v[14:15], v[12:13], v[10:11]
	v_and_b32_e32 v13, 0xffff0000, v91
	v_and_b32_e32 v12, 0xffff0000, v90
	v_pk_fma_f32 v[6:7], v[6:7], v[12:13], v[8:9]
	v_lshlrev_b32_e32 v9, 16, v93
	v_lshlrev_b32_e32 v8, 16, v92
	v_and_b32_e32 v14, 0xffff0000, v104
	v_and_b32_e32 v15, 0xffff0000, v105
	s_waitcnt vmcnt(5)
; __device__ __forceinline__ float bflo(unsigned v) { return __uint_as_float(v << 16); }
; __device__ __forceinline__ float bfhi(unsigned v) { return __uint_as_float(v & 0xffff0000u); }
; __device__ __forceinline__ unsigned pack2(float a, float b) { return (unsigned)f2bf(a) | ((unsigned)f2bf(b) << 16); }
; __device__ void odd_tiles(int tid_, int bid_, int nblk_, const Params& p, int oi, int mode, bool skip_ctx, char* smem) {
;     ...
; #pragma unroll
;     for (int i = 0; i < 5; ++i) {
;       int e = tid + i * 256, t = e / 40, c4 = (e % 40) * 4;
;       float4 acc = *(const float4*)(p.od_conv_b + oi * DC + cb + c4);
; #pragma unroll
;       for (int j = 0; j < 4; ++j) {
;         uint2 xv = xr[i][j];
;         float4 wv = *(const float4*)(p.od_conv_w + ((size_t)oi * 4 + j) * DC + cb + c4);
;         acc.x += bflo(xv.x) * wv.x; acc.y += bfhi(xv.x) * wv.y; acc.z += bflo(xv.y) * wv.z; acc.w += bfhi(xv.y) * wv.w;
;       }
;       uint2 o;
;       o.x = pack2(acc.x, acc.y);
;       o.y = pack2(acc.z, acc.w);
;       *(uint2*)(sU + t * 168 + c4) = o;
;     }
	v_mov_b32_e32 v2, v40
	v_mov_b32_e32 v3, v41
	v_mov_b32_e32 v4, v42
	v_mov_b32_e32 v5, v43
	v_mov_b32_e32 v12, v2
	v_mov_b32_e32 v13, v4
	v_pk_fma_f32 v[8:9], v[12:13], v[8:9], v[10:11]
	v_and_b32_e32 v11, 0xffff0000, v93
	v_and_b32_e32 v10, 0xffff0000, v92
	v_mov_b32_e32 v4, v3
	v_pk_fma_f32 v[2:3], v[4:5], v[10:11], v[6:7]
	v_and_b32_sdwa v1, v9, v198 dst_sel:DWORD dst_unused:UNUSED_PAD src0_sel:WORD_1 src1_sel:DWORD
	v_and_b32_sdwa v5, v3, v198 dst_sel:DWORD dst_unused:UNUSED_PAD src0_sel:WORD_1 src1_sel:DWORD
	v_and_b32_sdwa v6, v2, v198 dst_sel:DWORD dst_unused:UNUSED_PAD src0_sel:WORD_1 src1_sel:DWORD
	v_and_b32_sdwa v4, v8, v198 dst_sel:DWORD dst_unused:UNUSED_PAD src0_sel:WORD_1 src1_sel:DWORD
	v_add3_u32 v3, v3, v5, s63
	v_add3_u32 v2, v2, v6, s63
	v_add3_u32 v4, v8, v4, s63
	v_add3_u32 v1, v9, v1, s63
	v_and_b32_e32 v3, 0xffff0000, v3
	v_and_b32_e32 v2, 0xffff0000, v2
	v_or_b32_sdwa v3, v3, v1 dst_sel:DWORD dst_unused:UNUSED_PAD src0_sel:DWORD src1_sel:WORD_1
	v_or_b32_sdwa v2, v2, v4 dst_sel:DWORD dst_unused:UNUSED_PAD src0_sel:DWORD src1_sel:WORD_1
	ds_write_b64 v171, v[2:3]
	v_lshlrev_b64 v[2:3], 2, v[106:107]
	v_lshl_add_u64 v[4:5], s[20:21], 0, v[2:3]
	v_lshl_add_u64 v[2:3], s[22:23], 0, v[2:3]
	v_lshl_add_u64 v[10:11], v[2:3], 0, s[60:61]
	s_nop 0
	v_lshlrev_b64 v[64:65], 2, v[108:109]
	v_lshl_add_u64 v[66:67], s[20:21], 0, v[64:65]
	v_lshl_add_u64 v[64:65], s[22:23], 0, v[64:65]
	v_lshl_add_u64 v[64:65], v[64:65], 0, s[60:61]
	global_load_dwordx4 v[24:27], v[66:67], off
	global_load_dwordx4 v[28:31], v[64:65], off
	v_add_co_u32_e32 v20, vcc, 0x2800, v64
	s_nop 1
	v_addc_co_u32_e32 v21, vcc, 0, v65, vcc
	global_load_dwordx4 v[32:35], v[20:21], off
	v_add_co_u32_e32 v20, vcc, 0x5000, v64
	s_nop 1
	v_addc_co_u32_e32 v21, vcc, 0, v65, vcc
	global_load_dwordx4 v[36:39], v[20:21], off
	v_add_co_u32_e32 v20, vcc, 0x7800, v64
	s_nop 1
	v_addc_co_u32_e32 v21, vcc, 0, v65, vcc
	global_load_dwordx4 v[40:43], v[20:21], off
	v_lshlrev_b32_e32 v12, 16, v104
	v_lshlrev_b32_e32 v13, 16, v105
	s_waitcnt vmcnt(9)
	v_mov_b32_e32 v2, v44
	v_mov_b32_e32 v3, v45
	v_mov_b32_e32 v4, v46
	v_mov_b32_e32 v5, v47
	v_mov_b32_e32 v18, v2
	s_waitcnt vmcnt(8)
	v_mov_b32_e32 v6, v48
	v_mov_b32_e32 v7, v49
	v_mov_b32_e32 v8, v50
	v_mov_b32_e32 v9, v51
	v_mov_b32_e32 v17, v8
	v_mov_b32_e32 v19, v4
	v_mov_b32_e32 v8, v7
	v_mov_b32_e32 v4, v3
	v_mov_b32_e32 v16, v6
	v_pk_fma_f32 v[6:7], v[8:9], v[14:15], v[4:5]
	v_pk_fma_f32 v[12:13], v[16:17], v[12:13], v[18:19]
	v_lshlrev_b32_e32 v9, 16, v111
	v_lshlrev_b32_e32 v8, 16, v110
	s_waitcnt vmcnt(7)
	v_mov_b32_e32 v2, v52
	v_mov_b32_e32 v3, v53
	v_mov_b32_e32 v4, v54
	v_mov_b32_e32 v5, v55
	v_mov_b32_e32 v14, v2
	v_mov_b32_e32 v15, v4
	v_pk_fma_f32 v[8:9], v[14:15], v[8:9], v[12:13]
	v_and_b32_e32 v13, 0xffff0000, v111
	v_and_b32_e32 v12, 0xffff0000, v110
	v_mov_b32_e32 v4, v3
	v_pk_fma_f32 v[6:7], v[4:5], v[12:13], v[6:7]
	v_lshlrev_b32_e32 v13, 16, v123
	v_lshlrev_b32_e32 v12, 16, v122
	s_waitcnt vmcnt(6)
	v_mov_b32_e32 v2, v56
	v_mov_b32_e32 v3, v57
	v_mov_b32_e32 v4, v58
	v_mov_b32_e32 v5, v59
	v_mov_b32_e32 v14, v2
	v_mov_b32_e32 v15, v4
	v_pk_fma_f32 v[8:9], v[14:15], v[12:13], v[8:9]
	v_and_b32_e32 v13, 0xffff0000, v123
	v_and_b32_e32 v12, 0xffff0000, v122
	v_mov_b32_e32 v4, v3
	v_pk_fma_f32 v[6:7], v[4:5], v[12:13], v[6:7]
	v_lshlrev_b32_e32 v11, 16, v137
	v_lshlrev_b32_e32 v10, 16, v136
	v_and_b32_e32 v14, 0xffff0000, v138
	v_and_b32_e32 v15, 0xffff0000, v139
	s_waitcnt vmcnt(5)
; __device__ __forceinline__ float bflo(unsigned v) { return __uint_as_float(v << 16); }
; __device__ __forceinline__ float bfhi(unsigned v) { return __uint_as_float(v & 0xffff0000u); }
; __device__ __forceinline__ unsigned pack2(float a, float b) { return (unsigned)f2bf(a) | ((unsigned)f2bf(b) << 16); }
; __device__ void odd_tiles(int tid_, int bid_, int nblk_, const Params& p, int oi, int mode, bool skip_ctx, char* smem) {
;     ...
; #pragma unroll
;     for (int i = 0; i < 5; ++i) {
;       int e = tid + i * 256, t = e / 40, c4 = (e % 40) * 4;
;       float4 acc = *(const float4*)(p.od_conv_b + oi * DC + cb + c4);
; #pragma unroll
;       for (int j = 0; j < 4; ++j) {
;         uint2 xv = xr[i][j];
;         float4 wv = *(const float4*)(p.od_conv_w + ((size_t)oi * 4 + j) * DC + cb + c4);
;         acc.x += bflo(xv.x) * wv.x; acc.y += bfhi(xv.x) * wv.y; acc.z += bflo(xv.y) * wv.z; acc.w += bfhi(xv.y) * wv.w;
;       }
;       uint2 o;
;       o.x = pack2(acc.x, acc.y);
;       o.y = pack2(acc.z, acc.w);
;       *(uint2*)(sU + t * 168 + c4) = o;
;     }
;     lds_barrier();
;     int nxt = tile + nblk_;
;     while (nxt < ntiles && skip_ctx && ((nxt >> 4) % NCH) < 8) nxt += nblk_;
;     if (nxt < ntiles) ODD_PREFETCH(nxt)
	v_mov_b32_e32 v2, v60
	v_mov_b32_e32 v3, v61
	v_mov_b32_e32 v4, v62
	v_mov_b32_e32 v5, v63
	v_mov_b32_e32 v12, v2
	v_mov_b32_e32 v13, v4
	v_pk_fma_f32 v[8:9], v[12:13], v[10:11], v[8:9]
	v_and_b32_e32 v11, 0xffff0000, v137
	v_and_b32_e32 v10, 0xffff0000, v136
	v_mov_b32_e32 v4, v3
	v_pk_fma_f32 v[2:3], v[4:5], v[10:11], v[6:7]
	v_and_b32_sdwa v1, v9, v198 dst_sel:DWORD dst_unused:UNUSED_PAD src0_sel:WORD_1 src1_sel:DWORD
	v_and_b32_sdwa v5, v3, v198 dst_sel:DWORD dst_unused:UNUSED_PAD src0_sel:WORD_1 src1_sel:DWORD
	v_and_b32_sdwa v6, v2, v198 dst_sel:DWORD dst_unused:UNUSED_PAD src0_sel:WORD_1 src1_sel:DWORD
	v_and_b32_sdwa v4, v8, v198 dst_sel:DWORD dst_unused:UNUSED_PAD src0_sel:WORD_1 src1_sel:DWORD
	v_add3_u32 v3, v3, v5, s63
	v_add3_u32 v2, v2, v6, s63
	v_add3_u32 v4, v8, v4, s63
	v_add3_u32 v1, v9, v1, s63
	v_and_b32_e32 v3, 0xffff0000, v3
	v_and_b32_e32 v2, 0xffff0000, v2
	v_or_b32_sdwa v3, v3, v1 dst_sel:DWORD dst_unused:UNUSED_PAD src0_sel:DWORD src1_sel:WORD_1
	v_or_b32_sdwa v2, v2, v4 dst_sel:DWORD dst_unused:UNUSED_PAD src0_sel:DWORD src1_sel:WORD_1
	ds_write_b64 v173, v[2:3]
	v_lshlrev_b64 v[2:3], 2, v[108:109]
	v_lshl_add_u64 v[4:5], s[20:21], 0, v[2:3]
	v_lshl_add_u64 v[2:3], s[22:23], 0, v[2:3]
	v_lshl_add_u64 v[10:11], v[2:3], 0, s[60:61]
	s_nop 0
	v_lshlrev_b32_e32 v12, 16, v138
	v_lshlrev_b32_e32 v13, 16, v139
	v_readlane_b32 s20, v252, 13
	v_readlane_b32 s22, v252, 15
	s_add_i32 s27, s27, s22
	s_cmpk_gt_i32 s27, 0x21ff
	s_cselect_b64 s[86:87], -1, 0
	v_readlane_b32 s21, v252, 14
	v_readlane_b32 s23, v252, 16
	s_waitcnt vmcnt(4)
	v_mov_b32_e32 v2, v24
	v_mov_b32_e32 v3, v25
	v_mov_b32_e32 v4, v26
	v_mov_b32_e32 v5, v27
	v_mov_b32_e32 v18, v2
	s_waitcnt vmcnt(3)
	v_mov_b32_e32 v6, v28
	v_mov_b32_e32 v7, v29
	v_mov_b32_e32 v8, v30
	v_mov_b32_e32 v9, v31
	v_mov_b32_e32 v17, v8
	v_mov_b32_e32 v19, v4
	v_mov_b32_e32 v8, v7
	v_mov_b32_e32 v4, v3
	v_mov_b32_e32 v16, v6
	v_pk_fma_f32 v[6:7], v[8:9], v[14:15], v[4:5]
	v_pk_fma_f32 v[12:13], v[16:17], v[12:13], v[18:19]
	v_lshlrev_b32_e32 v9, 16, v141
	v_lshlrev_b32_e32 v8, 16, v140
	s_waitcnt vmcnt(2)
	v_mov_b32_e32 v2, v32
	v_mov_b32_e32 v3, v33
	v_mov_b32_e32 v4, v34
	v_mov_b32_e32 v5, v35
	v_mov_b32_e32 v14, v2
	v_mov_b32_e32 v15, v4
	v_pk_fma_f32 v[12:13], v[14:15], v[8:9], v[12:13]
	v_and_b32_e32 v9, 0xffff0000, v141
	v_and_b32_e32 v8, 0xffff0000, v140
	v_mov_b32_e32 v4, v3
	v_pk_fma_f32 v[2:3], v[4:5], v[8:9], v[6:7]
	s_nop 1
	v_lshlrev_b32_e32 v5, 16, v143
	v_lshlrev_b32_e32 v4, 16, v142
	s_waitcnt vmcnt(1)
	v_mov_b32_e32 v6, v36
	v_mov_b32_e32 v7, v37
	v_mov_b32_e32 v8, v38
	v_mov_b32_e32 v9, v39
	v_mov_b32_e32 v14, v6
	v_mov_b32_e32 v15, v8
	v_pk_fma_f32 v[4:5], v[14:15], v[4:5], v[12:13]
	v_and_b32_e32 v13, 0xffff0000, v143
	v_and_b32_e32 v12, 0xffff0000, v142
	v_mov_b32_e32 v8, v7
	v_pk_fma_f32 v[2:3], v[8:9], v[12:13], v[2:3]
	v_lshlrev_b32_e32 v11, 16, v145
	v_lshlrev_b32_e32 v10, 16, v144
	s_and_b64 vcc, exec, s[86:87]
	s_waitcnt vmcnt(0)
	v_mov_b32_e32 v6, v40
	v_mov_b32_e32 v7, v41
	v_mov_b32_e32 v8, v42
	v_mov_b32_e32 v9, v43
	v_mov_b32_e32 v12, v6
	v_mov_b32_e32 v13, v8
	v_pk_fma_f32 v[4:5], v[12:13], v[10:11], v[4:5]
	v_and_b32_e32 v11, 0xffff0000, v145
	v_and_b32_e32 v10, 0xffff0000, v144
	v_mov_b32_e32 v8, v7
	v_pk_fma_f32 v[2:3], v[8:9], v[10:11], v[2:3]
	v_and_b32_sdwa v1, v5, v198 dst_sel:DWORD dst_unused:UNUSED_PAD src0_sel:WORD_1 src1_sel:DWORD
	v_and_b32_sdwa v6, v4, v198 dst_sel:DWORD dst_unused:UNUSED_PAD src0_sel:WORD_1 src1_sel:DWORD
	v_add3_u32 v4, v4, v6, s63
	v_add3_u32 v1, v5, v1, s63
	v_and_b32_sdwa v5, v3, v198 dst_sel:DWORD dst_unused:UNUSED_PAD src0_sel:WORD_1 src1_sel:DWORD
	v_and_b32_sdwa v6, v2, v198 dst_sel:DWORD dst_unused:UNUSED_PAD src0_sel:WORD_1 src1_sel:DWORD
	v_add3_u32 v3, v3, v5, s63
	v_add3_u32 v2, v2, v6, s63
	v_and_b32_e32 v3, 0xffff0000, v3
	v_and_b32_e32 v2, 0xffff0000, v2
	v_or_b32_sdwa v3, v3, v1 dst_sel:DWORD dst_unused:UNUSED_PAD src0_sel:DWORD src1_sel:WORD_1
	v_or_b32_sdwa v2, v2, v4 dst_sel:DWORD dst_unused:UNUSED_PAD src0_sel:DWORD src1_sel:WORD_1
	ds_write_b64 v175, v[2:3]
	s_waitcnt lgkmcnt(0)
	s_barrier
	s_cbranch_vccnz .LBB0_275
	s_ashr_i32 s20, s27, 4
	s_mul_hi_i32 s21, s20, 0x78787879
	s_lshr_b32 s22, s21, 31
	s_ashr_i32 s21, s21, 6
	s_add_i32 s22, s21, s22
	s_mul_i32 s21, s22, 0x88
	s_sub_i32 s23, s20, s21
	s_cmp_gt_i32 s23, 7
	s_mov_b64 s[20:21], -1
	s_cbranch_scc0 .LBB0_232
	s_lshl_b32 s20, s23, 5
	s_lshl_b32 s34, s22, 12
	s_add_i32 s36, s20, 0xffffff00
	s_mov_b64 s[20:21], 0
